# v40 + scan C loop: chunk-top LDS reads reordered by first use (decay vectors first) with counted lgkmcnt waits
# baseline (speedup 1.0000x reference)
.LBB0_580:
	ds_read_b128 v[202:205], v82 offset:128
	ds_read_b128 v[186:189], v82 offset:64
	ds_read_b128 v[182:185], v82
	ds_read_b64_tr_b16 v[170:171], v84 offset:7008
	ds_read_b64_tr_b16 v[30:31], v83
	v_add_u32_e32 v83, 0x3700, v83
	ds_read2st64_b64 v[194:197], v85 offset1:1
	ds_read_b128 v[198:201], v43
	ds_read2_b64 v[190:193], v42 offset0:8 offset1:12
	ds_read_b64_tr_b16 v[162:163], v84 offset:6944
	ds_read2_b64 v[178:181], v42 offset1:4
	ds_read_b64_tr_b16 v[166:167], v84 offset:6976
	ds_read_b64_tr_b16 v[158:159], v84 offset:6912
	ds_read_b64_tr_b16 v[38:39], v84 offset:4608
	s_waitcnt lgkmcnt(12)
	v_pk_mul_f32 v[16:17], v[16:17], v[202:203]
	v_add_u32_e32 v202, 0x800, v42
	v_add_u32_e32 v42, 0x3700, v42
	v_pk_mul_f32 v[18:19], v[18:19], v[204:205]
	s_waitcnt lgkmcnt(11)
	v_pk_mul_f32 v[14:15], v[14:15], v[188:189]
	v_cvt_pk_f16_f32 v189, v18, v19
	v_cvt_pk_f16_f32 v188, v16, v17
	s_waitcnt lgkmcnt(10)
	v_pk_mul_f32 v[6:7], v[6:7], v[184:185]
	v_pk_mul_f32 v[4:5], v[4:5], v[182:183]
	ds_read2st64_b64 v[182:185], v85 offset0:2 offset1:3
	v_add_u32_e32 v85, 0x3700, v85
	s_waitcnt lgkmcnt(9)
	v_mfma_f32_16x16x16_f16 v[170:173], v[170:171], v[30:31], v[16:19]
	v_pk_mul_f32 v[12:13], v[12:13], v[186:187]
	s_waitcnt lgkmcnt(8)
	v_mfma_f32_16x16x16_f16 v[16:19], v[194:195], v[30:31], 0
	s_waitcnt lgkmcnt(7)
	v_mul_f32_e64 v2, v2, v200
	v_mul_f32_e64 v3, v3, v201
	v_pk_mul_f32 v[0:1], v[0:1], v[198:199]
	v_cvt_pk_f16_f32 v187, v14, v15
	v_cvt_pk_f16_f32 v186, v12, v13
	v_cvt_pk_f16_f32 v201, v6, v7
	v_cvt_pk_f16_f32 v199, v2, v3
	v_cvt_pk_f16_f32 v200, v4, v5
	v_cvt_pk_f16_f32 v198, v0, v1
	s_waitcnt lgkmcnt(6)
	v_mfma_f32_16x16x32_f16 v[190:193], v[190:193], v[186:189], 0
	s_waitcnt lgkmcnt(5)
	v_mfma_f32_16x16x16_f16 v[162:165], v[162:163], v[30:31], v[4:7]
	s_waitcnt lgkmcnt(4)
	v_mfma_f32_16x16x32_f16 v[4:7], v[178:181], v[198:201], v[16:19]
	s_waitcnt lgkmcnt(3)
	v_mfma_f32_16x16x16_f16 v[12:15], v[166:167], v[30:31], v[12:15]
	ds_read_b64_tr_b16 v[174:175], v84 offset:4640
	ds_read2_b64 v[166:169], v202 offset0:40 offset1:44
	ds_read_b64_tr_b16 v[22:23], v84 offset:4672
	s_nop 3
	v_pk_add_f32 v[6:7], v[6:7], v[192:193]
	v_pk_add_f32 v[4:5], v[4:5], v[190:191]
	v_cvt_pk_f16_f32 v35, v6, v7
	v_cvt_pk_f16_f32 v34, v4, v5
	s_waitcnt lgkmcnt(3)
	s_nop 0
	v_mfma_f32_16x16x16_f16 v[4:7], v[184:185], v[34:35], 0
	v_mfma_f32_16x16x16_f16 v[158:161], v[158:159], v[30:31], v[0:3]
	s_nop 6
	s_waitcnt lgkmcnt(1)
	v_mfma_f32_16x16x32_f16 v[0:3], v[166:169], v[186:189], 0
	v_cvt_pk_f16_f32 v19, -v6, -v7
	v_cvt_pk_f16_f32 v18, -v4, -v5
	v_mfma_f32_16x16x16_f16 v[6:9], v[196:197], v[30:31], 0
	s_add_i32 s24, s24, -1
	v_mfma_f32_16x16x16_f16 v[30:33], v[38:39], v[18:19], v[158:161]
	ds_read_b64_tr_b16 v[26:27], v84 offset:4704
	v_add_u32_e32 v84, 0x3700, v84
	ds_read_b128 v[38:41], v43 offset:256
	v_add_u32_e32 v43, 0x3700, v43
	s_nop 0
	ds_read_b128 v[158:161], v82 offset:256
	v_mfma_f32_16x16x16_f16 v[34:37], v[174:175], v[18:19], v[162:165]
	s_waitcnt lgkmcnt(3)
	v_mfma_f32_16x16x16_f16 v[12:15], v[22:23], v[18:19], v[12:15]
	ds_read_b128 v[22:25], v82 offset:320
	ds_read_b128 v[162:165], v82 offset:384
	v_add_u32_e32 v82, 0x3700, v82
	v_mfma_f32_16x16x16_f16 v[166:169], v[182:183], v[18:19], v[0:3]
	s_waitcnt lgkmcnt(2)
	v_pk_mul_f32 v[4:5], v[158:159], v[34:35]
	ds_read2_b64 v[0:3], v202 offset0:32 offset1:36
	v_mfma_f32_16x16x16_f16 v[26:29], v[26:27], v[18:19], v[170:173]
	s_waitcnt lgkmcnt(2)
	v_pk_mul_f32 v[14:15], v[24:25], v[14:15]
	v_pk_mul_f32 v[12:13], v[22:23], v[12:13]
	s_waitcnt lgkmcnt(0)
	v_mfma_f32_16x16x32_f16 v[170:173], v[0:3], v[198:201], v[6:9]
	v_mul_f32_e64 v2, v40, v32
	v_mul_f32_e64 v3, v41, v33
	v_pk_mul_f32 v[0:1], v[38:39], v[30:31]
	v_pk_mul_f32 v[6:7], v[160:161], v[36:37]
	v_pk_mul_f32 v[18:19], v[164:165], v[28:29]
	v_pk_mul_f32 v[16:17], v[162:163], v[26:27]
	s_nop 1
	v_pk_add_f32 v[20:21], v[170:171], v[166:167]
	v_pk_add_f32 v[8:9], v[172:173], v[168:169]
	ds_write2st64_b32 v86, v20, v21 offset1:1
	ds_write2st64_b32 v86, v8, v9 offset0:2 offset1:3
	v_add_u32_e32 v86, 0x1000, v86
	s_cmp_lg_u32 s24, 0
	s_cbranch_scc1 .LBB0_580
